# adds: P0 silu(c) precompute loop issues 16 loads per trip instead of one serialized load-wait per element
# speedup vs baseline: 1.0251x; 1.0042x over previous
.LBB0_10:
	s_mov_b32 s28, 4
.Lsilu_loop:
	global_load_dword v16, v[2:3], off
	v_lshl_add_u64 v[2:3], v[2:3], 0, s[10:11]
	global_load_dword v17, v[2:3], off
	v_lshl_add_u64 v[2:3], v[2:3], 0, s[10:11]
	global_load_dword v18, v[2:3], off
	v_lshl_add_u64 v[2:3], v[2:3], 0, s[10:11]
	global_load_dword v19, v[2:3], off
	v_lshl_add_u64 v[2:3], v[2:3], 0, s[10:11]
	global_load_dword v20, v[2:3], off
	v_lshl_add_u64 v[2:3], v[2:3], 0, s[10:11]
	global_load_dword v21, v[2:3], off
	v_lshl_add_u64 v[2:3], v[2:3], 0, s[10:11]
	global_load_dword v22, v[2:3], off
	v_lshl_add_u64 v[2:3], v[2:3], 0, s[10:11]
	global_load_dword v23, v[2:3], off
	v_lshl_add_u64 v[2:3], v[2:3], 0, s[10:11]
	global_load_dword v24, v[2:3], off
	v_lshl_add_u64 v[2:3], v[2:3], 0, s[10:11]
	global_load_dword v25, v[2:3], off
	v_lshl_add_u64 v[2:3], v[2:3], 0, s[10:11]
	global_load_dword v26, v[2:3], off
	v_lshl_add_u64 v[2:3], v[2:3], 0, s[10:11]
	global_load_dword v27, v[2:3], off
	v_lshl_add_u64 v[2:3], v[2:3], 0, s[10:11]
	global_load_dword v28, v[2:3], off
	v_lshl_add_u64 v[2:3], v[2:3], 0, s[10:11]
	global_load_dword v29, v[2:3], off
	v_lshl_add_u64 v[2:3], v[2:3], 0, s[10:11]
	global_load_dword v30, v[2:3], off
	v_lshl_add_u64 v[2:3], v[2:3], 0, s[10:11]
	global_load_dword v31, v[2:3], off
	v_lshl_add_u64 v[2:3], v[2:3], 0, s[10:11]
	s_waitcnt vmcnt(0)
	v_mul_f32_e32 v7, 0xbfb8aa3b, v16
	v_exp_f32_e32 v7, v7
	s_nop 0
	v_add_f32_e32 v7, 1.0, v7
	v_div_scale_f32 v8, s[68:69], v7, v7, v16
	v_rcp_f32_e32 v9, v8
	v_div_scale_f32 v10, vcc, v16, v7, v16
	v_fma_f32 v11, -v8, v9, 1.0
	v_fmac_f32_e32 v9, v11, v9
	v_mul_f32_e32 v11, v10, v9
	v_fma_f32 v12, -v8, v11, v10
	v_fmac_f32_e32 v11, v12, v9
	v_fma_f32 v8, -v8, v11, v10
	v_div_fmas_f32 v8, v8, v9, v11
	v_div_fixup_f32 v16, v8, v7, v16
	ds_write_b32 v4, v16
	v_mul_f32_e32 v7, 0xbfb8aa3b, v17
	v_exp_f32_e32 v7, v7
	s_nop 0
	v_add_f32_e32 v7, 1.0, v7
	v_div_scale_f32 v8, s[68:69], v7, v7, v17
	v_rcp_f32_e32 v9, v8
	v_div_scale_f32 v10, vcc, v17, v7, v17
	v_fma_f32 v11, -v8, v9, 1.0
	v_fmac_f32_e32 v9, v11, v9
	v_mul_f32_e32 v11, v10, v9
	v_fma_f32 v12, -v8, v11, v10
	v_fmac_f32_e32 v11, v12, v9
	v_fma_f32 v8, -v8, v11, v10
	v_div_fmas_f32 v8, v8, v9, v11
	v_div_fixup_f32 v17, v8, v7, v17
	ds_write_b32 v4, v17 offset:2048
	v_mul_f32_e32 v7, 0xbfb8aa3b, v18
	v_exp_f32_e32 v7, v7
	s_nop 0
	v_add_f32_e32 v7, 1.0, v7
	v_div_scale_f32 v8, s[68:69], v7, v7, v18
	v_rcp_f32_e32 v9, v8
	v_div_scale_f32 v10, vcc, v18, v7, v18
	v_fma_f32 v11, -v8, v9, 1.0
	v_fmac_f32_e32 v9, v11, v9
	v_mul_f32_e32 v11, v10, v9
	v_fma_f32 v12, -v8, v11, v10
	v_fmac_f32_e32 v11, v12, v9
	v_fma_f32 v8, -v8, v11, v10
	v_div_fmas_f32 v8, v8, v9, v11
	v_div_fixup_f32 v18, v8, v7, v18
	ds_write_b32 v4, v18 offset:4096
	v_mul_f32_e32 v7, 0xbfb8aa3b, v19
	v_exp_f32_e32 v7, v7
	s_nop 0
	v_add_f32_e32 v7, 1.0, v7
	v_div_scale_f32 v8, s[68:69], v7, v7, v19
	v_rcp_f32_e32 v9, v8
	v_div_scale_f32 v10, vcc, v19, v7, v19
	v_fma_f32 v11, -v8, v9, 1.0
	v_fmac_f32_e32 v9, v11, v9
	v_mul_f32_e32 v11, v10, v9
	v_fma_f32 v12, -v8, v11, v10
	v_fmac_f32_e32 v11, v12, v9
	v_fma_f32 v8, -v8, v11, v10
	v_div_fmas_f32 v8, v8, v9, v11
	v_div_fixup_f32 v19, v8, v7, v19
	ds_write_b32 v4, v19 offset:6144
	v_mul_f32_e32 v7, 0xbfb8aa3b, v20
	v_exp_f32_e32 v7, v7
	s_nop 0
	v_add_f32_e32 v7, 1.0, v7
	v_div_scale_f32 v8, s[68:69], v7, v7, v20
	v_rcp_f32_e32 v9, v8
	v_div_scale_f32 v10, vcc, v20, v7, v20
	v_fma_f32 v11, -v8, v9, 1.0
	v_fmac_f32_e32 v9, v11, v9
	v_mul_f32_e32 v11, v10, v9
	v_fma_f32 v12, -v8, v11, v10
	v_fmac_f32_e32 v11, v12, v9
	v_fma_f32 v8, -v8, v11, v10
	v_div_fmas_f32 v8, v8, v9, v11
	v_div_fixup_f32 v20, v8, v7, v20
	ds_write_b32 v4, v20 offset:8192
	v_mul_f32_e32 v7, 0xbfb8aa3b, v21
	v_exp_f32_e32 v7, v7
	s_nop 0
	v_add_f32_e32 v7, 1.0, v7
	v_div_scale_f32 v8, s[68:69], v7, v7, v21
	v_rcp_f32_e32 v9, v8
	v_div_scale_f32 v10, vcc, v21, v7, v21
	v_fma_f32 v11, -v8, v9, 1.0
	v_fmac_f32_e32 v9, v11, v9
	v_mul_f32_e32 v11, v10, v9
	v_fma_f32 v12, -v8, v11, v10
	v_fmac_f32_e32 v11, v12, v9
	v_fma_f32 v8, -v8, v11, v10
	v_div_fmas_f32 v8, v8, v9, v11
	v_div_fixup_f32 v21, v8, v7, v21
	ds_write_b32 v4, v21 offset:10240
	v_mul_f32_e32 v7, 0xbfb8aa3b, v22
	v_exp_f32_e32 v7, v7
	s_nop 0
	v_add_f32_e32 v7, 1.0, v7
	v_div_scale_f32 v8, s[68:69], v7, v7, v22
	v_rcp_f32_e32 v9, v8
	v_div_scale_f32 v10, vcc, v22, v7, v22
	v_fma_f32 v11, -v8, v9, 1.0
	v_fmac_f32_e32 v9, v11, v9
	v_mul_f32_e32 v11, v10, v9
	v_fma_f32 v12, -v8, v11, v10
	v_fmac_f32_e32 v11, v12, v9
	v_fma_f32 v8, -v8, v11, v10
	v_div_fmas_f32 v8, v8, v9, v11
	v_div_fixup_f32 v22, v8, v7, v22
	ds_write_b32 v4, v22 offset:12288
	v_mul_f32_e32 v7, 0xbfb8aa3b, v23
	v_exp_f32_e32 v7, v7
	s_nop 0
	v_add_f32_e32 v7, 1.0, v7
	v_div_scale_f32 v8, s[68:69], v7, v7, v23
	v_rcp_f32_e32 v9, v8
	v_div_scale_f32 v10, vcc, v23, v7, v23
	v_fma_f32 v11, -v8, v9, 1.0
	v_fmac_f32_e32 v9, v11, v9
	v_mul_f32_e32 v11, v10, v9
	v_fma_f32 v12, -v8, v11, v10
	v_fmac_f32_e32 v11, v12, v9
	v_fma_f32 v8, -v8, v11, v10
	v_div_fmas_f32 v8, v8, v9, v11
	v_div_fixup_f32 v23, v8, v7, v23
	ds_write_b32 v4, v23 offset:14336
	v_mul_f32_e32 v7, 0xbfb8aa3b, v24
	v_exp_f32_e32 v7, v7
	s_nop 0
	v_add_f32_e32 v7, 1.0, v7
	v_div_scale_f32 v8, s[68:69], v7, v7, v24
	v_rcp_f32_e32 v9, v8
	v_div_scale_f32 v10, vcc, v24, v7, v24
	v_fma_f32 v11, -v8, v9, 1.0
	v_fmac_f32_e32 v9, v11, v9
	v_mul_f32_e32 v11, v10, v9
	v_fma_f32 v12, -v8, v11, v10
	v_fmac_f32_e32 v11, v12, v9
	v_fma_f32 v8, -v8, v11, v10
	v_div_fmas_f32 v8, v8, v9, v11
	v_div_fixup_f32 v24, v8, v7, v24
	ds_write_b32 v4, v24 offset:16384
	v_mul_f32_e32 v7, 0xbfb8aa3b, v25
	v_exp_f32_e32 v7, v7
	s_nop 0
	v_add_f32_e32 v7, 1.0, v7
	v_div_scale_f32 v8, s[68:69], v7, v7, v25
	v_rcp_f32_e32 v9, v8
	v_div_scale_f32 v10, vcc, v25, v7, v25
	v_fma_f32 v11, -v8, v9, 1.0
	v_fmac_f32_e32 v9, v11, v9
	v_mul_f32_e32 v11, v10, v9
	v_fma_f32 v12, -v8, v11, v10
	v_fmac_f32_e32 v11, v12, v9
	v_fma_f32 v8, -v8, v11, v10
	v_div_fmas_f32 v8, v8, v9, v11
	v_div_fixup_f32 v25, v8, v7, v25
	ds_write_b32 v4, v25 offset:18432
	v_mul_f32_e32 v7, 0xbfb8aa3b, v26
	v_exp_f32_e32 v7, v7
	s_nop 0
	v_add_f32_e32 v7, 1.0, v7
	v_div_scale_f32 v8, s[68:69], v7, v7, v26
	v_rcp_f32_e32 v9, v8
	v_div_scale_f32 v10, vcc, v26, v7, v26
	v_fma_f32 v11, -v8, v9, 1.0
	v_fmac_f32_e32 v9, v11, v9
	v_mul_f32_e32 v11, v10, v9
	v_fma_f32 v12, -v8, v11, v10
	v_fmac_f32_e32 v11, v12, v9
	v_fma_f32 v8, -v8, v11, v10
	v_div_fmas_f32 v8, v8, v9, v11
	v_div_fixup_f32 v26, v8, v7, v26
	ds_write_b32 v4, v26 offset:20480
	v_mul_f32_e32 v7, 0xbfb8aa3b, v27
	v_exp_f32_e32 v7, v7
	s_nop 0
	v_add_f32_e32 v7, 1.0, v7
	v_div_scale_f32 v8, s[68:69], v7, v7, v27
	v_rcp_f32_e32 v9, v8
	v_div_scale_f32 v10, vcc, v27, v7, v27
	v_fma_f32 v11, -v8, v9, 1.0
	v_fmac_f32_e32 v9, v11, v9
	v_mul_f32_e32 v11, v10, v9
	v_fma_f32 v12, -v8, v11, v10
	v_fmac_f32_e32 v11, v12, v9
	v_fma_f32 v8, -v8, v11, v10
	v_div_fmas_f32 v8, v8, v9, v11
	v_div_fixup_f32 v27, v8, v7, v27
	ds_write_b32 v4, v27 offset:22528
	v_mul_f32_e32 v7, 0xbfb8aa3b, v28
	v_exp_f32_e32 v7, v7
	s_nop 0
	v_add_f32_e32 v7, 1.0, v7
	v_div_scale_f32 v8, s[68:69], v7, v7, v28
	v_rcp_f32_e32 v9, v8
	v_div_scale_f32 v10, vcc, v28, v7, v28
	v_fma_f32 v11, -v8, v9, 1.0
	v_fmac_f32_e32 v9, v11, v9
	v_mul_f32_e32 v11, v10, v9
	v_fma_f32 v12, -v8, v11, v10
	v_fmac_f32_e32 v11, v12, v9
	v_fma_f32 v8, -v8, v11, v10
	v_div_fmas_f32 v8, v8, v9, v11
	v_div_fixup_f32 v28, v8, v7, v28
	ds_write_b32 v4, v28 offset:24576
	v_mul_f32_e32 v7, 0xbfb8aa3b, v29
	v_exp_f32_e32 v7, v7
	s_nop 0
	v_add_f32_e32 v7, 1.0, v7
	v_div_scale_f32 v8, s[68:69], v7, v7, v29
	v_rcp_f32_e32 v9, v8
	v_div_scale_f32 v10, vcc, v29, v7, v29
	v_fma_f32 v11, -v8, v9, 1.0
	v_fmac_f32_e32 v9, v11, v9
	v_mul_f32_e32 v11, v10, v9
	v_fma_f32 v12, -v8, v11, v10
	v_fmac_f32_e32 v11, v12, v9
	v_fma_f32 v8, -v8, v11, v10
	v_div_fmas_f32 v8, v8, v9, v11
	v_div_fixup_f32 v29, v8, v7, v29
	ds_write_b32 v4, v29 offset:26624
	v_mul_f32_e32 v7, 0xbfb8aa3b, v30
	v_exp_f32_e32 v7, v7
	s_nop 0
	v_add_f32_e32 v7, 1.0, v7
	v_div_scale_f32 v8, s[68:69], v7, v7, v30
	v_rcp_f32_e32 v9, v8
	v_div_scale_f32 v10, vcc, v30, v7, v30
	v_fma_f32 v11, -v8, v9, 1.0
	v_fmac_f32_e32 v9, v11, v9
	v_mul_f32_e32 v11, v10, v9
	v_fma_f32 v12, -v8, v11, v10
	v_fmac_f32_e32 v11, v12, v9
	v_fma_f32 v8, -v8, v11, v10
	v_div_fmas_f32 v8, v8, v9, v11
	v_div_fixup_f32 v30, v8, v7, v30
	ds_write_b32 v4, v30 offset:28672
	v_mul_f32_e32 v7, 0xbfb8aa3b, v31
	v_exp_f32_e32 v7, v7
	s_nop 0
	v_add_f32_e32 v7, 1.0, v7
	v_div_scale_f32 v8, s[68:69], v7, v7, v31
	v_rcp_f32_e32 v9, v8
	v_div_scale_f32 v10, vcc, v31, v7, v31
	v_fma_f32 v11, -v8, v9, 1.0
	v_fmac_f32_e32 v9, v11, v9
	v_mul_f32_e32 v11, v10, v9
	v_fma_f32 v12, -v8, v11, v10
	v_fmac_f32_e32 v11, v12, v9
	v_fma_f32 v8, -v8, v11, v10
	v_div_fmas_f32 v8, v8, v9, v11
	v_div_fixup_f32 v31, v8, v7, v31
	ds_write_b32 v4, v31 offset:30720
	v_add_u32_e32 v4, 0x8000, v4
	s_sub_u32 s28, s28, 1
	s_cmp_lg_u32 s28, 0
	s_cbranch_scc1 .Lsilu_loop
